# adds rolling two-group prefetch of the f32 residual rows in layer-0 out-projection epilogue
# speedup vs baseline: 1.0067x; 1.0002x over previous
; __device__ __forceinline__ float bf_lo(unsigned w) { return __uint_as_float(w << 16); }
; __device__ __forceinline__ float bf_hi(unsigned w) { return __uint_as_float(w & 0xffff0000u); }
;     __device__ __forceinline__ void fused(f32x4 (&acc)[2][2][4][2], const Unit& u, int wr, int wc, int fr, int fq, PG8_LAS unsigned char* lds, int wid, int lane) const {
;     ...
;         const int col0 = u.pn * BM + wc * 32 + 8 * fq, b = u.pm >> 4;
;         {
;             f32x4 gv[2][2];
; #pragma unroll
;             for (int bj = 0; bj < 2; ++bj)
; #pragma unroll
;                 for (int n = 0; n < 2; ++n) gv[bj][n] = *(const f32x4*)(g + (size_t)b * 6144 + col0 + bj * HALF + 4 * n);
; #pragma unroll
;             for (int ai = 0; ai < 2; ++ai)
; #pragma unroll
;                 for (int m = 0; m < 4; ++m) { const int r = ai * HALF + wr * 64 + m * 16 + fr; const size_t off = (size_t)(u.pm * BM + r) * 1024 + col0;
; #pragma unroll
;                     for (int bj = 0; bj < 2; ++bj) { f32x4 b0, b1;
;                         if (XIN_BF16) { const u32x4 w = *(const u32x4*)((const bf16_t*)xin + off + bj * HALF); b0 = (f32x4){bf_lo(w.x), bf_hi(w.x), bf_lo(w.y), bf_hi(w.y)}; b1 = (f32x4){bf_lo(w.z), bf_hi(w.z), bf_lo(w.w), bf_hi(w.w)}; }
;                         else { b0 = *(const f32x4*)((const float*)xin + off + bj * HALF); b1 = *(const f32x4*)((const float*)xin + off + bj * HALF + 4); }
;                         acc[ai][bj][m][0] = b0 + gv[bj][0] * acc[ai][bj][m][0]; acc[ai][bj][m][1] = b1 + gv[bj][1] * acc[ai][bj][m][1]; }
;                     asm volatile("" : "+v"(acc[ai][0][m][0]), "+v"(acc[ai][0][m][1]), "+v"(acc[ai][1][m][0]), "+v"(acc[ai][1][m][1]));
;                     if (m == 3) asm volatile("" ::: "memory"); }
.LBB0_732:
	s_lshl_b32 s6, s17, 5
	s_lshl_b32 s7, s10, 8
	v_lshrrev_b32_e32 v130, 1, v166
	s_or_b32 s6, s7, s6
	v_and_or_b32 v156, v130, 24, s6
	s_ashr_i32 s6, s16, 4
	s_mul_i32 s25, s6, 0x6000
	s_mul_hi_i32 s24, s6, 0x6000
	s_add_u32 s6, s12, s25
	s_addc_u32 s7, s13, s24
	s_lshl_b32 s30, s16, 8
	v_ashrrev_i32_e32 v157, 31, v156
	v_add_u32_e32 v154, s30, v170
	v_lshlrev_b64 v[158:159], 2, v[156:157]
	v_ashrrev_i32_e32 v155, 31, v154
	v_lshl_add_u64 v[134:135], s[6:7], 0, v[158:159]
	s_movk_i32 s8, 0x2000
	v_lshlrev_b64 v[136:137], 12, v[154:155]
	s_mov_b64 s[6:7], 0x2000
	v_add_co_u32_e32 v130, vcc, s8, v134
	v_lshl_add_u64 v[136:137], s[18:19], 0, v[136:137]
	s_nop 0
	v_addc_co_u32_e32 v131, vcc, 0, v135, vcc
	v_lshl_add_u64 v[142:143], v[136:137], 0, v[158:159]
	v_lshl_add_u64 v[144:145], v[134:135], 0, s[6:7]
	s_barrier
	v_mov_b64_e32 v[244:245], v[142:143]
	s_mov_b64 s[98:99], 0x10000
	v_lshl_add_u64 v[248:249], v[244:245], 0, s[98:99]
	global_load_dwordx4 v[228:231], v[248:249], off
	global_load_dwordx4 v[232:235], v[248:249], off offset:16
	global_load_dwordx4 v[236:239], v[248:249], off offset:512
	global_load_dwordx4 v[240:243], v[248:249], off offset:528
	s_mov_b64 s[98:99], 0x20000
	v_lshl_add_u64 v[248:249], v[244:245], 0, s[98:99]
	global_load_dwordx4 v[212:215], v[248:249], off
	global_load_dwordx4 v[216:219], v[248:249], off offset:16
	global_load_dwordx4 v[220:223], v[248:249], off offset:512
	global_load_dwordx4 v[224:227], v[248:249], off offset:528
	global_load_dwordx4 v[130:133], v[130:131], off
	s_nop 0
	global_load_dwordx4 v[146:149], v[142:143], off offset:16
	global_load_dwordx4 v[150:153], v[142:143], off
	global_load_dwordx4 v[138:141], v[144:145], off offset:16
	global_load_dwordx4 v[134:137], v[144:145], off offset:512
	global_load_dwordx4 v[162:165], v[142:143], off offset:512
	global_load_dwordx4 v[174:177], v[142:143], off offset:528
	s_nop 0
	global_load_dwordx4 v[142:145], v[144:145], off offset:528
	v_add_u32_e32 v160, 16, v154
	v_ashrrev_i32_e32 v161, 31, v160
	v_lshlrev_b64 v[168:169], 12, v[160:161]
	v_lshl_add_u64 v[168:169], s[18:19], 0, v[168:169]
	v_lshl_add_u64 v[168:169], v[168:169], 0, v[158:159]
	v_mbcnt_hi_u32_b32 v173, -1, v1
	s_lshl_b32 s6, s17, 3
	s_add_i32 s8, s6, 0
	s_waitcnt vmcnt(0)
	v_pk_fma_f32 v[120:121], v[120:121], v[136:137], v[164:165]
	v_pk_fma_f32 v[124:125], v[124:125], v[132:133], v[152:153]
	v_pk_fma_f32 v[122:123], v[122:123], v[130:131], v[150:151]
	v_pk_fma_f32 v[128:129], v[128:129], v[140:141], v[148:149]
	v_pk_fma_f32 v[126:127], v[126:127], v[138:139], v[146:147]
	v_pk_fma_f32 v[118:119], v[118:119], v[134:135], v[162:163]
	v_pk_fma_f32 v[116:117], v[116:117], v[144:145], v[176:177]
	v_pk_fma_f32 v[114:115], v[114:115], v[142:143], v[174:175]
	v_add_u32_e32 v162, 32, v154
	s_waitcnt vmcnt(4)
	v_mov_b32_e32 v146, v228
	v_mov_b32_e32 v147, v229
	v_mov_b32_e32 v148, v230
	v_mov_b32_e32 v149, v231
	v_mov_b32_e32 v150, v232
	v_mov_b32_e32 v151, v233
	v_mov_b32_e32 v152, v234
	v_mov_b32_e32 v153, v235
	v_mov_b32_e32 v174, v236
	v_mov_b32_e32 v175, v237
	v_mov_b32_e32 v176, v238
	v_mov_b32_e32 v177, v239
	v_mov_b32_e32 v178, v240
	v_mov_b32_e32 v179, v241
	v_mov_b32_e32 v180, v242
	v_mov_b32_e32 v181, v243
	s_mov_b64 s[98:99], 0x30000
	v_lshl_add_u64 v[248:249], v[244:245], 0, s[98:99]
	global_load_dwordx4 v[228:231], v[248:249], off
	global_load_dwordx4 v[232:235], v[248:249], off offset:16
	global_load_dwordx4 v[236:239], v[248:249], off offset:512
	global_load_dwordx4 v[240:243], v[248:249], off offset:528
	v_ashrrev_i32_e32 v163, 31, v162
	v_lshlrev_b64 v[164:165], 12, v[162:163]
	v_lshl_add_u64 v[164:165], s[18:19], 0, v[164:165]
	v_lshl_add_u64 v[164:165], v[164:165], 0, v[158:159]
	v_mov_b32_e32 v192, v123
	v_mov_b32_e32 v193, v124
	v_mov_b32_e32 v194, v122
	v_mov_b32_e32 v195, v125
	v_pk_add_f32 v[192:193], v[192:193], v[194:195]
	v_add_f32_e32 v197, v118, v119
	v_add_f32_e32 v192, v192, v193
	v_add_f32_e32 v199, v120, v121
	v_mov_b32_e32 v196, v114
	v_mov_b32_e32 v198, v115
	v_mov_b32_e32 v206, v117
	v_add_f32_e32 v207, 0, v192
	s_nop 0
	v_pk_fma_f32 v[112:113], v[112:113], v[132:133], v[148:149]
	v_pk_fma_f32 v[110:111], v[110:111], v[130:131], v[146:147]
	s_nop 0
	v_pk_fma_f32 v[108:109], v[108:109], v[140:141], v[152:153]
	v_pk_fma_f32 v[106:107], v[106:107], v[138:139], v[150:151]
	s_nop 0
	v_pk_fma_f32 v[72:73], v[72:73], v[136:137], v[176:177]
	v_pk_fma_f32 v[70:71], v[70:71], v[134:135], v[174:175]
	s_nop 0
	v_pk_fma_f32 v[68:69], v[68:69], v[144:145], v[180:181]
	v_pk_fma_f32 v[66:67], v[66:67], v[142:143], v[178:179]
	s_nop 0
	s_waitcnt vmcnt(4)
	v_mov_b32_e32 v146, v212
	v_mov_b32_e32 v147, v213
	v_mov_b32_e32 v148, v214
	v_mov_b32_e32 v149, v215
	v_mov_b32_e32 v150, v216
	v_mov_b32_e32 v151, v217
	v_mov_b32_e32 v152, v218
	v_mov_b32_e32 v153, v219
	v_mov_b32_e32 v174, v220
	v_mov_b32_e32 v175, v221
	v_mov_b32_e32 v176, v222
	v_mov_b32_e32 v177, v223
	v_mov_b32_e32 v178, v224
	v_mov_b32_e32 v179, v225
	v_mov_b32_e32 v180, v226
	v_mov_b32_e32 v181, v227
	s_mov_b64 s[98:99], 0x80000
	v_lshl_add_u64 v[248:249], v[244:245], 0, s[98:99]
	global_load_dwordx4 v[212:215], v[248:249], off
	global_load_dwordx4 v[216:219], v[248:249], off offset:16
	global_load_dwordx4 v[220:223], v[248:249], off offset:512
	global_load_dwordx4 v[224:227], v[248:249], off offset:528
	v_add_u32_e32 v164, 48, v154
	v_ashrrev_i32_e32 v165, 31, v164
	v_lshlrev_b64 v[168:169], 12, v[164:165]
	v_lshl_add_u64 v[168:169], s[18:19], 0, v[168:169]
	v_lshl_add_u64 v[168:169], v[168:169], 0, v[158:159]
	s_nop 0
	v_pk_fma_f32 v[104:105], v[104:105], v[132:133], v[148:149]
	v_pk_fma_f32 v[102:103], v[102:103], v[130:131], v[146:147]
	s_nop 0
	v_pk_fma_f32 v[100:101], v[100:101], v[140:141], v[152:153]
	v_pk_fma_f32 v[98:99], v[98:99], v[138:139], v[150:151]
	s_nop 0
	v_pk_fma_f32 v[64:65], v[64:65], v[136:137], v[176:177]
	v_pk_fma_f32 v[62:63], v[62:63], v[134:135], v[174:175]
	s_nop 0
	v_pk_fma_f32 v[60:61], v[60:61], v[144:145], v[180:181]
	v_pk_fma_f32 v[58:59], v[58:59], v[142:143], v[178:179]
	v_add_u32_e32 v150, 0x80, v154
	s_waitcnt vmcnt(4)
; __device__ __forceinline__ float bf_lo(unsigned w) { return __uint_as_float(w << 16); }
; __device__ __forceinline__ float bf_hi(unsigned w) { return __uint_as_float(w & 0xffff0000u); }
;     __device__ __forceinline__ void fused(f32x4 (&acc)[2][2][4][2], const Unit& u, int wr, int wc, int fr, int fq, PG8_LAS unsigned char* lds, int wid, int lane) const {
;     ...
;             for (int ai = 0; ai < 2; ++ai)
; #pragma unroll
;                 for (int m = 0; m < 4; ++m) { const int r = ai * HALF + wr * 64 + m * 16 + fr; const size_t off = (size_t)(u.pm * BM + r) * 1024 + col0;
; #pragma unroll
;                     for (int bj = 0; bj < 2; ++bj) { f32x4 b0, b1;
;                         if (XIN_BF16) { const u32x4 w = *(const u32x4*)((const bf16_t*)xin + off + bj * HALF); b0 = (f32x4){bf_lo(w.x), bf_hi(w.x), bf_lo(w.y), bf_hi(w.y)}; b1 = (f32x4){bf_lo(w.z), bf_hi(w.z), bf_lo(w.w), bf_hi(w.w)}; }
;                         else { b0 = *(const f32x4*)((const float*)xin + off + bj * HALF); b1 = *(const f32x4*)((const float*)xin + off + bj * HALF + 4); }
;                         acc[ai][bj][m][0] = b0 + gv[bj][0] * acc[ai][bj][m][0]; acc[ai][bj][m][1] = b1 + gv[bj][1] * acc[ai][bj][m][1]; }
;                     asm volatile("" : "+v"(acc[ai][0][m][0]), "+v"(acc[ai][0][m][1]), "+v"(acc[ai][1][m][0]), "+v"(acc[ai][1][m][1]));
;                     if (m == 3) asm volatile("" ::: "memory"); }
	v_mov_b32_e32 v146, v228
	v_mov_b32_e32 v147, v229
	v_mov_b32_e32 v148, v230
	v_mov_b32_e32 v149, v231
	v_mov_b32_e32 v174, v232
	v_mov_b32_e32 v175, v233
	v_mov_b32_e32 v176, v234
	v_mov_b32_e32 v177, v235
	v_mov_b32_e32 v178, v236
	v_mov_b32_e32 v179, v237
	v_mov_b32_e32 v180, v238
	v_mov_b32_e32 v181, v239
	v_mov_b32_e32 v182, v240
	v_mov_b32_e32 v183, v241
	v_mov_b32_e32 v184, v242
	v_mov_b32_e32 v185, v243
	s_mov_b64 s[98:99], 0x90000
	v_lshl_add_u64 v[248:249], v[244:245], 0, s[98:99]
	global_load_dwordx4 v[228:231], v[248:249], off
	global_load_dwordx4 v[232:235], v[248:249], off offset:16
	global_load_dwordx4 v[236:239], v[248:249], off offset:512
	global_load_dwordx4 v[240:243], v[248:249], off offset:528
	v_ashrrev_i32_e32 v151, 31, v150
	v_lshlrev_b64 v[152:153], 12, v[150:151]
	v_lshl_add_u64 v[152:153], s[18:19], 0, v[152:153]
	v_lshl_add_u64 v[152:153], v[152:153], 0, v[158:159]
	s_nop 0
	v_pk_fma_f32 v[96:97], v[96:97], v[132:133], v[148:149]
	v_pk_fma_f32 v[94:95], v[94:95], v[130:131], v[146:147]
	s_nop 0
	v_pk_fma_f32 v[92:93], v[92:93], v[140:141], v[176:177]
	v_pk_fma_f32 v[90:91], v[90:91], v[138:139], v[174:175]
	s_nop 0
	v_pk_fma_f32 v[56:57], v[56:57], v[136:137], v[180:181]
	v_pk_fma_f32 v[54:55], v[54:55], v[134:135], v[178:179]
	s_nop 0
	v_pk_fma_f32 v[52:53], v[52:53], v[144:145], v[184:185]
	v_pk_fma_f32 v[50:51], v[50:51], v[142:143], v[182:183]
	v_add_u32_e32 v148, 0x90, v154
	s_waitcnt vmcnt(4)
	v_mov_b32_e32 v174, v212
	v_mov_b32_e32 v175, v213
	v_mov_b32_e32 v176, v214
	v_mov_b32_e32 v177, v215
	v_mov_b32_e32 v178, v216
	v_mov_b32_e32 v179, v217
	v_mov_b32_e32 v180, v218
	v_mov_b32_e32 v181, v219
	v_mov_b32_e32 v182, v220
	v_mov_b32_e32 v183, v221
	v_mov_b32_e32 v184, v222
	v_mov_b32_e32 v185, v223
	v_mov_b32_e32 v186, v224
	v_mov_b32_e32 v187, v225
	v_mov_b32_e32 v188, v226
	v_mov_b32_e32 v189, v227
	s_mov_b64 s[98:99], 0xa0000
	v_lshl_add_u64 v[248:249], v[244:245], 0, s[98:99]
	global_load_dwordx4 v[212:215], v[248:249], off
	global_load_dwordx4 v[216:219], v[248:249], off offset:16
	global_load_dwordx4 v[220:223], v[248:249], off offset:512
	global_load_dwordx4 v[224:227], v[248:249], off offset:528
	v_ashrrev_i32_e32 v149, 31, v148
	v_lshlrev_b64 v[146:147], 12, v[148:149]
	v_lshl_add_u64 v[146:147], s[18:19], 0, v[146:147]
	v_lshl_add_u64 v[146:147], v[146:147], 0, v[158:159]
	s_nop 0
	v_pk_fma_f32 v[88:89], v[88:89], v[132:133], v[176:177]
	v_pk_fma_f32 v[86:87], v[86:87], v[130:131], v[174:175]
	s_nop 0
	v_pk_fma_f32 v[84:85], v[84:85], v[140:141], v[180:181]
	v_pk_fma_f32 v[82:83], v[82:83], v[138:139], v[178:179]
	s_nop 0
	v_pk_fma_f32 v[48:49], v[48:49], v[136:137], v[184:185]
	v_pk_fma_f32 v[46:47], v[46:47], v[134:135], v[182:183]
	s_nop 0
	v_pk_fma_f32 v[44:45], v[44:45], v[144:145], v[188:189]
	v_pk_fma_f32 v[42:43], v[42:43], v[142:143], v[186:187]
	s_nop 0
	s_waitcnt vmcnt(4)
	v_mov_b32_e32 v174, v228
	v_mov_b32_e32 v175, v229
	v_mov_b32_e32 v176, v230
	v_mov_b32_e32 v177, v231
	v_mov_b32_e32 v178, v232
	v_mov_b32_e32 v179, v233
	v_mov_b32_e32 v180, v234
	v_mov_b32_e32 v181, v235
	v_mov_b32_e32 v182, v236
	v_mov_b32_e32 v183, v237
	v_mov_b32_e32 v184, v238
	v_mov_b32_e32 v185, v239
	v_mov_b32_e32 v186, v240
	v_mov_b32_e32 v187, v241
	v_mov_b32_e32 v188, v242
	v_mov_b32_e32 v189, v243
	s_mov_b64 s[98:99], 0xb0000
	v_lshl_add_u64 v[248:249], v[244:245], 0, s[98:99]
	global_load_dwordx4 v[228:231], v[248:249], off
	global_load_dwordx4 v[232:235], v[248:249], off offset:16
	global_load_dwordx4 v[236:239], v[248:249], off offset:512
	global_load_dwordx4 v[240:243], v[248:249], off offset:528
	v_add_u32_e32 v146, 0xa0, v154
	v_ashrrev_i32_e32 v147, 31, v146
	v_lshlrev_b64 v[152:153], 12, v[146:147]
	v_lshl_add_u64 v[152:153], s[18:19], 0, v[152:153]
	v_lshl_add_u64 v[152:153], v[152:153], 0, v[158:159]
	s_nop 0
	v_pk_fma_f32 v[80:81], v[80:81], v[132:133], v[176:177]
	v_pk_fma_f32 v[78:79], v[78:79], v[130:131], v[174:175]
	s_nop 0
	v_pk_fma_f32 v[76:77], v[76:77], v[140:141], v[180:181]
	v_pk_fma_f32 v[74:75], v[74:75], v[138:139], v[178:179]
	s_nop 0
	v_pk_fma_f32 v[40:41], v[40:41], v[136:137], v[184:185]
	v_pk_fma_f32 v[38:39], v[38:39], v[134:135], v[182:183]
	s_nop 0
	v_pk_fma_f32 v[36:37], v[36:37], v[144:145], v[188:189]
	v_pk_fma_f32 v[34:35], v[34:35], v[142:143], v[186:187]
	s_nop 0
	s_waitcnt vmcnt(4)
; __device__ __forceinline__ float bf_lo(unsigned w) { return __uint_as_float(w << 16); }
;     template <class Mid> __device__ __forceinline__ bool run(const f32x4 (&v)[2][2][4][2], const Unit& u, int wr, int wc, int fr, int fq, PG8_LAS unsigned char* lds, int wid, int lane, const Mid& mid) const {
;     ...
;         for (int ai = 0; ai < 2; ++ai)
; #pragma unroll
;             for (int m = 0; m < 4; ++m) {
;                 float s = 0.f;
; #pragma unroll
;                 for (int bj = 0; bj < 2; ++bj)
; #pragma unroll
;                     for (int n = 0; n < 2; ++n) { const f32x4 x = v[ai][bj][m][n]; s += (x[0] + x[1]) + (x[2] + x[3]); }
;                 s += __shfl_xor(s, 16); s += __shfl_xor(s, 32);
;                 const float mw = s * (1.0f / 64.0f); float q = 0.f;
; #pragma unroll
;                 for (int bj = 0; bj < 2; ++bj)
; #pragma unroll
;                     for (int n = 0; n < 2; ++n) { const f32x4 d = v[ai][bj][m][n] - mw; q += (d[0] * d[0] + d[1] * d[1]) + (d[2] * d[2] + d[3] * d[3]); }
;                 q += __shfl_xor(q, 16); q += __shfl_xor(q, 32);
;                 if (fq == 0) P[(ai * HALF + wr * 64 + m * 16 + fr) * 4 + wc] = (f32x2v){mw, q};
;     __device__ __forceinline__ void fused(f32x4 (&acc)[2][2][4][2], const Unit& u, int wr, int wc, int fr, int fq, PG8_LAS unsigned char* lds, int wid, int lane) const {
;     ...
;                 for (int m = 0; m < 4; ++m) { const int r = ai * HALF + wr * 64 + m * 16 + fr; const size_t off = (size_t)(u.pm * BM + r) * 1024 + col0;
; #pragma unroll
;                     for (int bj = 0; bj < 2; ++bj) { f32x4 b0, b1;
;                         if (XIN_BF16) { const u32x4 w = *(const u32x4*)((const bf16_t*)xin + off + bj * HALF); b0 = (f32x4){bf_lo(w.x), bf_hi(w.x), bf_lo(w.y), bf_hi(w.y)}; b1 = (f32x4){bf_lo(w.z), bf_hi(w.z), bf_lo(w.w), bf_hi(w.w)}; }
;                         else { b0 = *(const f32x4*)((const float*)xin + off + bj * HALF); b1 = *(const f32x4*)((const float*)xin + off + bj * HALF + 4); }
;                         acc[ai][bj][m][0] = b0 + gv[bj][0] * acc[ai][bj][m][0]; acc[ai][bj][m][1] = b1 + gv[bj][1] * acc[ai][bj][m][1]; }
;                     asm volatile("" : "+v"(acc[ai][0][m][0]), "+v"(acc[ai][0][m][1]), "+v"(acc[ai][1][m][0]), "+v"(acc[ai][1][m][1]));
;                     if (m == 3) asm volatile("" ::: "memory"); }
	v_mov_b32_e32 v174, v212
	v_mov_b32_e32 v175, v213
	v_mov_b32_e32 v176, v214
	v_mov_b32_e32 v177, v215
	v_mov_b32_e32 v178, v216
	v_mov_b32_e32 v179, v217
	v_mov_b32_e32 v180, v218
	v_mov_b32_e32 v181, v219
	v_mov_b32_e32 v182, v220
	v_mov_b32_e32 v183, v221
	v_mov_b32_e32 v184, v222
	v_mov_b32_e32 v185, v223
	v_mov_b32_e32 v186, v224
	v_mov_b32_e32 v187, v225
	v_mov_b32_e32 v188, v226
	v_mov_b32_e32 v189, v227
	v_and_b32_e32 v153, 64, v173
	v_xor_b32_e32 v152, 16, v173
	v_add_u32_e32 v208, 64, v153
	v_cmp_lt_i32_e32 vcc, v152, v208
	s_nop 0
	v_pk_fma_f32 v[32:33], v[32:33], v[132:133], v[176:177]
	v_cndmask_b32_e32 v152, v173, v152, vcc
	v_lshlrev_b32_e32 v167, 2, v152
	v_add_u32_e32 v152, 0xb0, v154
	v_ashrrev_i32_e32 v153, 31, v152
	v_lshlrev_b64 v[168:169], 12, v[152:153]
	v_lshl_add_u64 v[168:169], s[18:19], 0, v[168:169]
	v_lshl_add_u64 v[168:169], v[168:169], 0, v[158:159]
	v_pk_fma_f32 v[30:31], v[30:31], v[130:131], v[174:175]
	s_nop 0
	v_pk_fma_f32 v[28:29], v[28:29], v[140:141], v[180:181]
	v_pk_fma_f32 v[26:27], v[26:27], v[138:139], v[178:179]
	s_nop 0
	v_pk_fma_f32 v[24:25], v[24:25], v[136:137], v[184:185]
	v_pk_fma_f32 v[22:23], v[22:23], v[134:135], v[182:183]
	s_nop 0
	v_pk_fma_f32 v[20:21], v[20:21], v[144:145], v[188:189]
	v_pk_fma_f32 v[18:19], v[18:19], v[142:143], v[186:187]
	v_mov_b32_e32 v174, v127
	s_waitcnt vmcnt(0)
	v_mov_b32_e32 v176, v232
	v_mov_b32_e32 v177, v233
	v_mov_b32_e32 v178, v234
	v_mov_b32_e32 v179, v235
	v_mov_b32_e32 v180, v228
	v_mov_b32_e32 v181, v229
	v_mov_b32_e32 v182, v230
	v_mov_b32_e32 v183, v231
	v_mov_b32_e32 v184, v240
	v_mov_b32_e32 v185, v241
	v_mov_b32_e32 v186, v242
	v_mov_b32_e32 v187, v243
	v_mov_b32_e32 v188, v236
	v_mov_b32_e32 v189, v237
	v_mov_b32_e32 v190, v238
	v_mov_b32_e32 v191, v239
	v_mov_b32_e32 v175, v128
	v_mov_b32_e32 v168, v126
	v_mov_b32_e32 v169, v129
	v_pk_add_f32 v[168:169], v[174:175], v[168:169]
	v_pk_add_f32 v[174:175], v[196:197], v[198:199]
	v_pk_add_f32 v[168:169], v[168:169], v[168:169] op_sel_hi:[0,1]
	v_mov_b32_e32 v168, v116
	v_pk_add_f32 v[168:169], v[168:169], v[206:207]
	s_nop 0
	v_pk_fma_f32 v[12:13], v[12:13], v[140:141], v[178:179]
	v_pk_add_f32 v[168:169], v[174:175], v[168:169]
	s_nop 0
	v_pk_fma_f32 v[16:17], v[16:17], v[132:133], v[182:183]
	v_add_f32_e32 v168, v168, v169
	ds_bpermute_b32 v174, v167, v168
	v_xor_b32_e32 v169, 32, v173
	v_cmp_lt_i32_e32 vcc, v169, v208
	v_pk_fma_f32 v[14:15], v[14:15], v[130:131], v[180:181]
	v_pk_fma_f32 v[10:11], v[10:11], v[138:139], v[176:177]
	v_cndmask_b32_e32 v169, v173, v169, vcc
	v_lshlrev_b32_e32 v169, 2, v169
	s_waitcnt lgkmcnt(0)
	v_add_f32_e32 v168, v168, v174
	ds_bpermute_b32 v173, v169, v168
	s_nop 0
	v_pk_fma_f32 v[8:9], v[8:9], v[136:137], v[190:191]
	v_pk_fma_f32 v[6:7], v[6:7], v[134:135], v[188:189]
	v_pk_fma_f32 v[4:5], v[4:5], v[144:145], v[186:187]
	v_pk_fma_f32 v[2:3], v[2:3], v[142:143], v[184:185]
	s_waitcnt lgkmcnt(0)
	v_add_f32_e32 v173, v168, v173
	v_fmamk_f32 v174, v173, 0xbc800000, v125
	v_fmamk_f32 v192, v173, 0xbc800000, v123
	v_fmamk_f32 v194, v173, 0xbc800000, v129
	v_fmamk_f32 v196, v173, 0xbc800000, v127
	v_fmamk_f32 v168, v173, 0xbc800000, v124
	v_fmamk_f32 v175, v173, 0xbc800000, v122
	v_fmamk_f32 v193, v173, 0xbc800000, v128
	v_fmamk_f32 v195, v173, 0xbc800000, v126
	v_fmamk_f32 v198, v173, 0xbc800000, v121
	v_fmamk_f32 v206, v173, 0xbc800000, v119
	v_mul_f32_e32 v192, v192, v192
	v_mul_f32_e32 v174, v174, v174
	v_mul_f32_e32 v196, v196, v196
	v_mul_f32_e32 v194, v194, v194
	v_fmamk_f32 v197, v173, 0xbc800000, v120
	v_fmamk_f32 v199, v173, 0xbc800000, v118
	v_fmamk_f32 v208, v173, 0xbc800000, v117
	v_fmamk_f32 v210, v173, 0xbc800000, v115
	v_mul_f32_e32 v206, v206, v206
	v_mul_f32_e32 v198, v198, v198
	v_fmac_f32_e32 v192, v175, v175
	v_fmac_f32_e32 v174, v168, v168
	v_fmac_f32_e32 v196, v195, v195
	v_fmac_f32_e32 v194, v193, v193
	v_fmamk_f32 v207, v173, 0xbc800000, v116
	v_fmamk_f32 v209, v173, 0xbc800000, v114
	v_mul_f32_e32 v210, v210, v210
	v_mul_f32_e32 v208, v208, v208
	v_fmac_f32_e32 v206, v199, v199
	v_fmac_f32_e32 v198, v197, v197
	v_add_f32_e32 v168, v192, v174
	v_add_f32_e32 v174, v196, v194
	v_fmac_f32_e32 v210, v209, v209
	v_fmac_f32_e32 v208, v207, v207
	v_add_f32_e32 v175, v206, v198
	v_add_f32_e32 v168, v168, v174
	v_add_f32_e32 v192, v210, v208
	v_add_f32_e32 v168, v175, v168
	v_add_f32_e32 v174, v192, v168
	ds_bpermute_b32 v175, v167, v174
	v_and_b32_e32 v168, 63, v166
	v_cmp_gt_u32_e32 vcc, 16, v168
	s_waitcnt lgkmcnt(0)
	v_add_f32_e32 v174, v174, v175
	ds_bpermute_b32 v175, v169, v174
	s_and_saveexec_b64 s[6:7], vcc
	s_cbranch_execz .LBB0_734
	s_lshl_b32 s9, s23, 11
	s_add_i32 s9, s8, s9
	v_mul_f32_e32 v130, 0x3c800000, v173
	s_waitcnt lgkmcnt(0)
	v_add_f32_e32 v131, v174, v175
	v_lshl_add_u32 v132, v171, 5, s9
	ds_write_b64 v132, v[130:131]
